# fox: key-side cumulative-gate bias read once per lane and broadcast with DPP row_newbcast (8x fewer LDS bias reads); lazy rescale threshold 64
# speedup vs baseline: 1.0055x; 1.0017x over previous
; #define LAS __attribute__((address_space(3)))
; #define GAS __attribute__((address_space(1)))
; template <int MODE> ...
;     ...
;         *(LAS f32x4*)(cbuf + 4 * tid) = (f32x4){ex + s1, ex + s2, ex + s3, ex + s4};
;         __syncthreads();
;         cq = cbuf[q];
;     }
;     if (MODE == 1) { if (tid < 8) flags[tid] = 0u; }
;     bf16x8 qr[4];
;     { const GAS bf16_t* qp = HA + (rowbase + q) * LDH + qcol + hi * 8;
; #pragma unroll
;       for (int d0 = 0; d0 < 4; ++d0) qr[d0] = *(const GAS bf16x8*)(qp + d0 * 16); }
;     bf16x8 T0, T1, ONES;
;     if (MODE == 1) {
; #pragma unroll
;         for (int j = 0; j < 8; ++j) { const int kk = 8 * (j >> 2) + 4 * hi + (j & 3); T0[j] = (kk > r32) ? (short)0x3F80 : (short)0; T1[j] = (16 + kk > r32) ? (short)0x3F80 : (short)0; ONES[j] = (short)0x3F80; }
;     }
;     LAS unsigned long long* mlds = (LAS unsigned long long*)(lds + 45568) + (wid * 32 + r32) * 33;
;     if (MODE == 2) {
;         const GAS unsigned long long* mbp = MB + (rowbase + q) * 32 + hi * 16;
;         u32x4 mw[8];
; #pragma unroll
;         for (int i = 0; i < 8; ++i) mw[i] = *(const GAS u32x4*)(mbp + 2 * i);
; #pragma unroll
;         for (int i = 0; i < 8; ++i) { mlds[hi * 16 + 2 * i] = ((unsigned long long)mw[i].y << 32) | mw[i].x; mlds[hi * 16 + 2 * i + 1] = ((unsigned long long)mw[i].w << 32) | mw[i].z; }
;     }
;     f32x16 zero16;
; #pragma unroll
;     for (int i = 0; i < 16; ++i) zero16[i] = 0.f;
;     f32x16 o0 = zero16, o1 = zero16;
;     float m = 0.f, l = 0.f, R = 0.f; bool uns = true;
.LBB0_823:
	s_mov_b64 s[0:1], 0x300
	v_lshl_add_u64 v[22:23], v[98:99], 0, s[0:1]
	s_mov_b64 s[0:1], 0x600
	v_readlane_b32 s7, v254, 7
	v_cmp_gt_u32_e32 vcc, 32, v11
	v_lshl_add_u64 v[24:25], v[98:99], 0, s[0:1]
	s_lshl_b32 s0, s7, 8
	s_lshl_b32 s1, s6, 5
	v_cndmask_b32_e32 v19, v20, v19, vcc
	v_and_b32_e32 v26, 31, v1
	s_add_i32 s6, s1, s0
	v_add_f32_e32 v19, v19, v21
	v_or_b32_e32 v102, s6, v26
	v_sub_f32_e32 v20, v19, v17
	v_readlane_b32 s0, v252, 56
	v_pk_add_f32 v[16:17], v[16:17], v[20:21] op_sel_hi:[1,0]
	v_pk_add_f32 v[14:15], v[14:15], v[20:21] op_sel_hi:[1,0]
	v_lshl_add_u32 v19, v1, 4, 0
	v_ashrrev_i32_e32 v103, 31, v102
	v_readlane_b32 s1, v252, 57
	ds_write_b128 v19, v[14:17] offset:36864
	v_lshl_add_u64 v[100:101], s[4:5], 0, v[102:103]
	v_mov_b64_e32 v[14:15], s[0:1]
	s_movk_i32 s4, 0x1880
	v_mad_u64_u32 v[14:15], s[0:1], v100, s4, v[14:15]
	v_lshrrev_b32_e32 v11, 5, v11
	v_mad_i32_i24 v15, v101, s4, v15
	v_lshl_add_u64 v[14:15], s[2:3], 1, v[14:15]
	v_lshlrev_b32_e32 v16, 4, v11
	v_mov_b32_e32 v17, v0
	v_lshl_add_u64 v[14:15], v[14:15], 0, v[16:17]
	s_mov_b32 s0, 0x62000
	s_waitcnt lgkmcnt(0)
	s_barrier
	global_load_dwordx4 v[66:69], v[14:15], off
	global_load_dwordx4 v[70:73], v[14:15], off offset:32
	global_load_dwordx4 v[74:77], v[14:15], off offset:64
	global_load_dwordx4 v[78:81], v[14:15], off offset:96
	v_add_co_u32_e32 v14, vcc, s0, v22
	s_movk_i32 s1, 0x90
	s_nop 0
	v_addc_co_u32_e32 v15, vcc, 0, v23, vcc
	v_add_co_u32_e32 v20, vcc, s0, v24
	v_lshlrev_b32_e32 v103, 2, v11
	s_nop 0
	v_addc_co_u32_e32 v21, vcc, 0, v25, vcc
	global_load_dwordx4 v[82:85], v[14:15], off
	global_load_dwordx4 v[86:89], v[20:21], off
	v_lshl_add_u32 v14, v102, 2, 0
	ds_read_b32 v105, v14 offset:36864
	v_mul_lo_u32 v14, v18, s1
	v_add3_u32 v107, 0, v14, v10
	ds_write_b128 v107, v[2:5]
	ds_write_b128 v107, v[6:9] offset:9216
	v_lshrrev_b32_e32 v2, 2, v1
	v_and_or_b32 v2, v2, 3, v103
	v_and_b32_e32 v1, 16, v1
	v_and_b32_e32 v3, 12, v12
	v_mad_u32_u24 v2, v2, s1, 0
	v_lshlrev_b32_e32 v1, 1, v1
	v_lshlrev_b32_e32 v3, 1, v3
	v_add3_u32 v108, v2, v1, v3
	v_xor_b32_e32 v1, 32, v224
	v_add_u32_e32 v2, 64, v13
	v_cmp_lt_i32_e32 vcc, v1, v2
	s_lshl_b32 s0, s7, 2
	v_add_u32_e32 v17, 0, v16
	v_mul_u32_u24_e32 v18, 0x90, v26
	v_cndmask_b32_e32 v1, v224, v1, vcc
	v_mov_b32_e32 v14, v0
	v_mov_b32_e32 v15, v0
	s_add_i32 s8, s0, 4
	s_or_b32 s10, s0, 3
	v_lshlrev_b32_e32 v109, 2, v1
	s_add_i32 s0, 0, 0x9000
	v_mov_b32_e32 v1, v0
	v_mov_b32_e32 v2, v0
	v_mov_b32_e32 v3, v0
	v_mov_b32_e32 v4, v0
	v_mov_b32_e32 v5, v0
	v_mov_b32_e32 v6, v0
	v_mov_b32_e32 v7, v0
	v_mov_b32_e32 v8, v0
	v_mov_b32_e32 v9, v0
	v_mov_b32_e32 v10, v0
	v_mov_b32_e32 v11, v0
	v_mov_b32_e32 v12, v0
	v_mov_b32_e32 v13, v0
	v_add_u32_e32 v113, v17, v18
	v_mov_b64_e32 v[32:33], v[14:15]
	s_ashr_i32 s9, s6, 6
	v_add_u32_e32 v110, s0, v16
	v_and_b32_e32 v128, 12, v224
	v_and_b32_e32 v129, 3, v224
	v_lshlrev_b32_e32 v128, 3, v128
	v_lshl_add_u32 v128, v129, 2, v128
	v_add_u32_e32 v110, v110, v128
	v_mov_b64_e32 v[30:31], v[12:13]
	v_mov_b64_e32 v[28:29], v[10:11]
	v_mov_b64_e32 v[26:27], v[8:9]
	v_mov_b64_e32 v[24:25], v[6:7]
	v_mov_b64_e32 v[22:23], v[4:5]
	v_mov_b64_e32 v[20:21], v[2:3]
	v_mov_b64_e32 v[18:19], v[0:1]
	v_mov_b64_e32 v[16:17], v[14:15]
	s_mov_b32 s13, 0
	s_add_i32 s11, s9, -1
	v_or_b32_e32 v111, 0x7b, v103
	s_mov_b64 s[0:1], -1
	v_mov_b32_e32 v112, 0
	v_mov_b64_e32 v[14:15], v[12:13]
	v_mov_b64_e32 v[12:13], v[10:11]
	v_mov_b64_e32 v[10:11], v[8:9]
	v_mov_b64_e32 v[8:9], v[6:7]
	v_mov_b64_e32 v[6:7], v[4:5]
	v_mov_b64_e32 v[4:5], v[2:3]
	v_mov_b64_e32 v[2:3], v[0:1]
	v_mov_b32_e32 v114, 0
	s_waitcnt lgkmcnt(0)
	s_barrier
.LBB0_824:
	s_add_i32 s12, s13, 2
	s_min_i32 s4, s12, s10
	s_mul_i32 s4, s4, 0x62000
	s_mov_b32 s5, 0
	v_lshl_add_u64 v[34:35], s[4:5], 0, v[98:99]
	global_load_dwordx4 v[90:93], v[34:35], off offset:768
	global_load_dwordx4 v[94:97], v[34:35], off offset:1536
	s_cmp_gt_i32 s13, s9
	s_cbranch_scc1 .LBB0_832
	ds_read_b32 v128, v110
	ds_read_b32 v129, v110 offset:128
	ds_read_b128 v[116:119], v113
	ds_read_b128 v[120:123], v113 offset:32
	ds_read_b128 v[124:127], v113 offset:64
	ds_read_b128 v[182:185], v113 offset:96
	ds_read_b128 v[186:189], v113 offset:4608
	ds_read_b128 v[190:193], v113 offset:4640
	ds_read_b128 v[242:245], v113 offset:4672
	ds_read_b128 v[246:249], v113 offset:4704
	v_sub_f32_e32 v1, v105, v112
	s_waitcnt lgkmcnt(8)
	v_subrev_f32_dpp v34, v128, v1 row_newbcast:0 row_mask:0xf bank_mask:0xf
	v_subrev_f32_dpp v35, v128, v1 row_newbcast:1 row_mask:0xf bank_mask:0xf
	v_subrev_f32_dpp v36, v128, v1 row_newbcast:2 row_mask:0xf bank_mask:0xf
	v_subrev_f32_dpp v37, v128, v1 row_newbcast:3 row_mask:0xf bank_mask:0xf
	v_subrev_f32_dpp v38, v128, v1 row_newbcast:4 row_mask:0xf bank_mask:0xf
	v_subrev_f32_dpp v39, v128, v1 row_newbcast:5 row_mask:0xf bank_mask:0xf
	v_subrev_f32_dpp v40, v128, v1 row_newbcast:6 row_mask:0xf bank_mask:0xf
	v_subrev_f32_dpp v41, v128, v1 row_newbcast:7 row_mask:0xf bank_mask:0xf
	v_subrev_f32_dpp v42, v128, v1 row_newbcast:8 row_mask:0xf bank_mask:0xf
	v_subrev_f32_dpp v43, v128, v1 row_newbcast:9 row_mask:0xf bank_mask:0xf
	v_subrev_f32_dpp v44, v128, v1 row_newbcast:10 row_mask:0xf bank_mask:0xf
	v_subrev_f32_dpp v45, v128, v1 row_newbcast:11 row_mask:0xf bank_mask:0xf
	v_subrev_f32_dpp v46, v128, v1 row_newbcast:12 row_mask:0xf bank_mask:0xf
	v_subrev_f32_dpp v47, v128, v1 row_newbcast:13 row_mask:0xf bank_mask:0xf
	v_subrev_f32_dpp v48, v128, v1 row_newbcast:14 row_mask:0xf bank_mask:0xf
	v_subrev_f32_dpp v49, v128, v1 row_newbcast:15 row_mask:0xf bank_mask:0xf
	s_waitcnt vmcnt(4) lgkmcnt(4)
	s_nop 0
	v_mfma_f32_32x32x16_bf16 v[34:49], v[116:119], v[66:69], v[34:49]
	v_subrev_f32_dpp v50, v129, v1 row_newbcast:0 row_mask:0xf bank_mask:0xf
	v_subrev_f32_dpp v51, v129, v1 row_newbcast:1 row_mask:0xf bank_mask:0xf
	v_subrev_f32_dpp v52, v129, v1 row_newbcast:2 row_mask:0xf bank_mask:0xf
	v_subrev_f32_dpp v53, v129, v1 row_newbcast:3 row_mask:0xf bank_mask:0xf
	s_waitcnt lgkmcnt(4)
	v_mfma_f32_32x32x16_bf16 v[34:49], v[120:123], v[70:73], v[34:49]
	v_subrev_f32_dpp v54, v129, v1 row_newbcast:4 row_mask:0xf bank_mask:0xf
	v_subrev_f32_dpp v55, v129, v1 row_newbcast:5 row_mask:0xf bank_mask:0xf
	v_subrev_f32_dpp v56, v129, v1 row_newbcast:6 row_mask:0xf bank_mask:0xf
	v_subrev_f32_dpp v57, v129, v1 row_newbcast:7 row_mask:0xf bank_mask:0xf
	s_waitcnt lgkmcnt(4)
	v_mfma_f32_32x32x16_bf16 v[34:49], v[124:127], v[74:77], v[34:49]
	v_subrev_f32_dpp v58, v129, v1 row_newbcast:8 row_mask:0xf bank_mask:0xf
	v_subrev_f32_dpp v59, v129, v1 row_newbcast:9 row_mask:0xf bank_mask:0xf
	v_subrev_f32_dpp v60, v129, v1 row_newbcast:10 row_mask:0xf bank_mask:0xf
	v_subrev_f32_dpp v61, v129, v1 row_newbcast:11 row_mask:0xf bank_mask:0xf
	s_waitcnt lgkmcnt(0)
	v_mfma_f32_32x32x16_bf16 v[34:49], v[182:185], v[78:81], v[34:49]
	v_subrev_f32_dpp v62, v129, v1 row_newbcast:12 row_mask:0xf bank_mask:0xf
	v_subrev_f32_dpp v63, v129, v1 row_newbcast:13 row_mask:0xf bank_mask:0xf
	v_subrev_f32_dpp v64, v129, v1 row_newbcast:14 row_mask:0xf bank_mask:0xf
	v_subrev_f32_dpp v65, v129, v1 row_newbcast:15 row_mask:0xf bank_mask:0xf
	s_nop 1
	v_mfma_f32_32x32x16_bf16 v[50:65], v[186:189], v[66:69], v[50:65]
	ds_read_b64_tr_b16 v[198:199], v108 offset:9216
	ds_read_b64_tr_b16 v[200:201], v108 offset:10368
	ds_read_b64_tr_b16 v[202:203], v108 offset:11520
	ds_read_b64_tr_b16 v[204:205], v108 offset:12672
	v_mfma_f32_32x32x16_bf16 v[50:65], v[190:193], v[70:73], v[50:65]
	ds_read_b64_tr_b16 v[206:207], v108 offset:13824
	ds_read_b64_tr_b16 v[208:209], v108 offset:14976
	ds_read_b64_tr_b16 v[210:211], v108 offset:16128
	ds_read_b64_tr_b16 v[212:213], v108 offset:17280
	v_mfma_f32_32x32x16_bf16 v[50:65], v[242:245], v[74:77], v[50:65]
	ds_read_b64_tr_b16 v[214:215], v108 offset:9280
	ds_read_b64_tr_b16 v[216:217], v108 offset:10432
	ds_read_b64_tr_b16 v[218:219], v108 offset:11584
	ds_read_b64_tr_b16 v[220:221], v108 offset:12736
	v_mfma_f32_32x32x16_bf16 v[50:65], v[246:249], v[78:81], v[50:65]
	ds_read_b64_tr_b16 v[234:235], v108 offset:13888
	ds_read_b64_tr_b16 v[236:237], v108 offset:15040
	ds_read_b64_tr_b16 v[238:239], v108 offset:16192
	ds_read_b64_tr_b16 v[240:241], v108 offset:17344
	s_nop 1
	s_cmp_lg_u32 s9, s13
	s_cbranch_scc1 .LBB0_827
	v_add_u32_e32 v104, 0xffffffa5, v111
	v_add_u32_e32 v1, 0xffffff85, v111
	v_cmp_le_i32_e32 vcc, v104, v102
	s_nop 7
	v_cndmask_b32_e32 v50, v232, v50, vcc
	v_cmp_lt_i32_e32 vcc, v1, v102
	s_nop 1
	v_cndmask_b32_e32 v35, v232, v35, vcc
	v_cmp_le_i32_e32 vcc, v1, v102
	v_add_u32_e32 v1, 0xffffffa6, v111
	s_nop 0
	v_cndmask_b32_e32 v34, v232, v34, vcc
	v_cmp_le_i32_e32 vcc, v1, v102
	v_add_u32_e32 v1, 0xffffff87, v111
	s_nop 0
	v_cndmask_b32_e32 v51, v232, v51, vcc
	v_cmp_le_i32_e32 vcc, v1, v102
	v_add_u32_e32 v1, 0xffffffa7, v111
	s_nop 0
	v_cndmask_b32_e32 v36, v232, v36, vcc
	v_cmp_le_i32_e32 vcc, v1, v102
	v_add_u32_e32 v1, 0xffffff88, v111
	s_nop 0
	v_cndmask_b32_e32 v52, v232, v52, vcc
	v_cmp_le_i32_e32 vcc, v1, v102
	v_add_u32_e32 v1, 0xffffffa8, v111
	s_nop 0
	v_cndmask_b32_e32 v37, v232, v37, vcc
	v_cmp_le_i32_e32 vcc, v1, v102
	v_add_u32_e32 v1, 0xffffff8d, v111
	s_nop 0
	v_cndmask_b32_e32 v53, v232, v53, vcc
	v_cmp_le_i32_e32 vcc, v1, v102
	v_add_u32_e32 v1, 0xffffffad, v111
	s_nop 0
	v_cndmask_b32_e32 v38, v232, v38, vcc
	v_cmp_le_i32_e32 vcc, v1, v102
	v_add_u32_e32 v1, 0xffffff8e, v111
	s_nop 0
	v_cndmask_b32_e32 v54, v232, v54, vcc
	v_cmp_le_i32_e32 vcc, v1, v102
	v_add_u32_e32 v1, 0xffffffae, v111
	s_nop 0
	v_cndmask_b32_e32 v39, v232, v39, vcc
	v_cmp_le_i32_e32 vcc, v1, v102
	v_add_u32_e32 v1, 0xffffff8f, v111
	s_nop 0
	v_cndmask_b32_e32 v55, v232, v55, vcc
	v_cmp_le_i32_e32 vcc, v1, v102
	v_add_u32_e32 v1, 0xffffffaf, v111
	s_nop 0
	v_cndmask_b32_e32 v40, v232, v40, vcc
	v_cmp_le_i32_e32 vcc, v1, v102
	v_add_u32_e32 v1, 0xffffff90, v111
	s_nop 0
	v_cndmask_b32_e32 v56, v232, v56, vcc
	v_cmp_le_i32_e32 vcc, v1, v102
	v_add_u32_e32 v1, 0xffffffb0, v111
	s_nop 0
	v_cndmask_b32_e32 v41, v232, v41, vcc
	v_cmp_le_i32_e32 vcc, v1, v102
	v_add_u32_e32 v1, 0xffffff95, v111
	s_nop 0
	v_cndmask_b32_e32 v57, v232, v57, vcc
	v_cmp_le_i32_e32 vcc, v1, v102
	v_add_u32_e32 v1, 0xffffffb5, v111
	s_nop 0
	v_cndmask_b32_e32 v42, v232, v42, vcc
	v_cmp_le_i32_e32 vcc, v1, v102
	v_add_u32_e32 v1, 0xffffff96, v111
	s_nop 0
	v_cndmask_b32_e32 v58, v232, v58, vcc
	v_cmp_le_i32_e32 vcc, v1, v102
	v_add_u32_e32 v1, 0xffffffb6, v111
	s_nop 0
	v_cndmask_b32_e32 v43, v232, v43, vcc
	v_cmp_le_i32_e32 vcc, v1, v102
	v_add_u32_e32 v1, 0xffffff97, v111
	s_nop 0
	v_cndmask_b32_e32 v59, v232, v59, vcc
	v_cmp_le_i32_e32 vcc, v1, v102
	v_add_u32_e32 v1, 0xffffffb7, v111
	s_nop 0
	v_cndmask_b32_e32 v44, v232, v44, vcc
	v_cmp_le_i32_e32 vcc, v1, v102
	v_add_u32_e32 v1, 0xffffff98, v111
	s_nop 0
	v_cndmask_b32_e32 v60, v232, v60, vcc
	v_cmp_le_i32_e32 vcc, v1, v102
	v_add_u32_e32 v1, 0xffffffb8, v111
	s_nop 0
	v_cndmask_b32_e32 v45, v232, v45, vcc
	v_cmp_le_i32_e32 vcc, v1, v102
	v_add_u32_e32 v1, 0xffffff9d, v111
	s_nop 0
	v_cndmask_b32_e32 v61, v232, v61, vcc
	v_cmp_le_i32_e32 vcc, v1, v102
	v_add_u32_e32 v1, 0xffffffbd, v111
	s_nop 0
	v_cndmask_b32_e32 v46, v232, v46, vcc
	v_cmp_le_i32_e32 vcc, v1, v102
	v_add_u32_e32 v1, 0xffffff9e, v111
	s_nop 0
	v_cndmask_b32_e32 v62, v232, v62, vcc
	v_cmp_le_i32_e32 vcc, v1, v102
	v_add_u32_e32 v1, 0xffffffbe, v111
	s_nop 0
	v_cndmask_b32_e32 v47, v232, v47, vcc
	v_cmp_le_i32_e32 vcc, v1, v102
	v_add_u32_e32 v1, 0xffffff9f, v111
	s_nop 0
	v_cndmask_b32_e32 v63, v232, v63, vcc
	v_cmp_le_i32_e32 vcc, v1, v102
	v_add_u32_e32 v1, 0xffffffbf, v111
	s_nop 0
	v_cndmask_b32_e32 v48, v232, v48, vcc
	v_cmp_le_i32_e32 vcc, v1, v102
	v_add_u32_e32 v1, 0xffffffa0, v111
	s_nop 0
	v_cndmask_b32_e32 v64, v232, v64, vcc
	v_cmp_le_i32_e32 vcc, v1, v102
	v_subrev_u32_e32 v1, 64, v111
	s_nop 0
	v_cndmask_b32_e32 v49, v232, v49, vcc
	v_cmp_le_i32_e32 vcc, v1, v102
	s_nop 1
	v_cndmask_b32_e32 v65, v232, v65, vcc

; #define LAS __attribute__((address_space(3)))
; #define STAGE_TILE(bufi, KR, VR) do { LAS bf16_t* Ks_ = (LAS bf16_t*)(lds + (bufi) * 18432); LAS bf16_t* Vs_ = (LAS bf16_t*)(lds + (bufi) * 18432 + 9216); \
;         *(LAS u32x4*)(Ks_ + skr * 72 + sch * 8) = KR; *(LAS u32x4*)(Vs_ + skr * 72 + sch * 8) = VR; } while (0)
; #define LOAD_TILE(KR, VR, tl) do { KR = *(const GAS u32x4*)(kg + (size_t)(tl) * 64 * LDH); VR = *(const GAS u32x4*)(vg + (size_t)(tl) * 64 * LDH); } while (0)
; template <int MODE> ...
;     ...
;         STAGE_TILE(1, kB, vB);
;         __syncthreads();
;         if (MODE == 1) { const u32x4 fa = *(const LAS u32x4*)flags, fb = *(const LAS u32x4*)(flags + 4); if ((fa.x & fa.y & fa.z & fa.w & fb.x & fb.y & fb.z & fb.w) != 0u) break; }
;         LOAD_TILE(kB, vB, TILE_OF(min(it + 3, ntiles - 1)));
;         COMPUTE_TILE(TILE_OF(it + 1), 1);
.LBB0_832:
	s_add_i32 s4, s13, 3
	s_min_i32 s4, s4, s10
	s_mul_i32 s4, s4, 0x62000
	s_mov_b32 s5, 0
	v_lshl_add_u64 v[34:35], s[4:5], 0, v[98:99]
	s_waitcnt vmcnt(3)
	ds_write_b128 v107, v[82:85] offset:18432
	s_waitcnt vmcnt(2)
	ds_write_b128 v107, v[86:89] offset:27648
	s_waitcnt lgkmcnt(0)
	s_barrier
	global_load_dwordx4 v[82:85], v[34:35], off offset:768
	global_load_dwordx4 v[86:89], v[34:35], off offset:1536
	s_cmp_ge_i32 s13, s9
	s_cbranch_scc1 .LBB0_840
	ds_read_b32 v128, v110 offset:256
	ds_read_b32 v129, v110 offset:384
	ds_read_b128 v[116:119], v113 offset:18432
	ds_read_b128 v[120:123], v113 offset:18464
	ds_read_b128 v[124:127], v113 offset:18496
	ds_read_b128 v[182:185], v113 offset:18528
	ds_read_b128 v[186:189], v113 offset:23040
	ds_read_b128 v[190:193], v113 offset:23072
	ds_read_b128 v[242:245], v113 offset:23104
	ds_read_b128 v[246:249], v113 offset:23136
	v_sub_f32_e32 v1, v105, v112
	s_waitcnt lgkmcnt(8)
	v_subrev_f32_dpp v34, v128, v1 row_newbcast:0 row_mask:0xf bank_mask:0xf
	v_subrev_f32_dpp v35, v128, v1 row_newbcast:1 row_mask:0xf bank_mask:0xf
	v_subrev_f32_dpp v36, v128, v1 row_newbcast:2 row_mask:0xf bank_mask:0xf
	v_subrev_f32_dpp v37, v128, v1 row_newbcast:3 row_mask:0xf bank_mask:0xf
	v_subrev_f32_dpp v38, v128, v1 row_newbcast:4 row_mask:0xf bank_mask:0xf
	v_subrev_f32_dpp v39, v128, v1 row_newbcast:5 row_mask:0xf bank_mask:0xf
	v_subrev_f32_dpp v40, v128, v1 row_newbcast:6 row_mask:0xf bank_mask:0xf
	v_subrev_f32_dpp v41, v128, v1 row_newbcast:7 row_mask:0xf bank_mask:0xf
	v_subrev_f32_dpp v42, v128, v1 row_newbcast:8 row_mask:0xf bank_mask:0xf
	v_subrev_f32_dpp v43, v128, v1 row_newbcast:9 row_mask:0xf bank_mask:0xf
	v_subrev_f32_dpp v44, v128, v1 row_newbcast:10 row_mask:0xf bank_mask:0xf
	v_subrev_f32_dpp v45, v128, v1 row_newbcast:11 row_mask:0xf bank_mask:0xf
	v_subrev_f32_dpp v46, v128, v1 row_newbcast:12 row_mask:0xf bank_mask:0xf
	v_subrev_f32_dpp v47, v128, v1 row_newbcast:13 row_mask:0xf bank_mask:0xf
	v_subrev_f32_dpp v48, v128, v1 row_newbcast:14 row_mask:0xf bank_mask:0xf
	v_subrev_f32_dpp v49, v128, v1 row_newbcast:15 row_mask:0xf bank_mask:0xf
	s_waitcnt lgkmcnt(4)
	s_nop 0
	v_mfma_f32_32x32x16_bf16 v[34:49], v[116:119], v[66:69], v[34:49]
	v_subrev_f32_dpp v50, v129, v1 row_newbcast:0 row_mask:0xf bank_mask:0xf
	v_subrev_f32_dpp v51, v129, v1 row_newbcast:1 row_mask:0xf bank_mask:0xf
	v_subrev_f32_dpp v52, v129, v1 row_newbcast:2 row_mask:0xf bank_mask:0xf
	v_subrev_f32_dpp v53, v129, v1 row_newbcast:3 row_mask:0xf bank_mask:0xf
	s_waitcnt lgkmcnt(4)
	v_mfma_f32_32x32x16_bf16 v[34:49], v[120:123], v[70:73], v[34:49]
	v_subrev_f32_dpp v54, v129, v1 row_newbcast:4 row_mask:0xf bank_mask:0xf
	v_subrev_f32_dpp v55, v129, v1 row_newbcast:5 row_mask:0xf bank_mask:0xf
	v_subrev_f32_dpp v56, v129, v1 row_newbcast:6 row_mask:0xf bank_mask:0xf
	v_subrev_f32_dpp v57, v129, v1 row_newbcast:7 row_mask:0xf bank_mask:0xf
	s_waitcnt lgkmcnt(4)
	v_mfma_f32_32x32x16_bf16 v[34:49], v[124:127], v[74:77], v[34:49]
	v_subrev_f32_dpp v58, v129, v1 row_newbcast:8 row_mask:0xf bank_mask:0xf
	v_subrev_f32_dpp v59, v129, v1 row_newbcast:9 row_mask:0xf bank_mask:0xf
	v_subrev_f32_dpp v60, v129, v1 row_newbcast:10 row_mask:0xf bank_mask:0xf
	v_subrev_f32_dpp v61, v129, v1 row_newbcast:11 row_mask:0xf bank_mask:0xf
	s_waitcnt lgkmcnt(0)
	v_mfma_f32_32x32x16_bf16 v[34:49], v[182:185], v[78:81], v[34:49]
	v_subrev_f32_dpp v62, v129, v1 row_newbcast:12 row_mask:0xf bank_mask:0xf
	v_subrev_f32_dpp v63, v129, v1 row_newbcast:13 row_mask:0xf bank_mask:0xf
	v_subrev_f32_dpp v64, v129, v1 row_newbcast:14 row_mask:0xf bank_mask:0xf
	v_subrev_f32_dpp v65, v129, v1 row_newbcast:15 row_mask:0xf bank_mask:0xf
	s_nop 1
	v_mfma_f32_32x32x16_bf16 v[50:65], v[186:189], v[66:69], v[50:65]
	ds_read_b64_tr_b16 v[198:199], v108 offset:27648
	ds_read_b64_tr_b16 v[200:201], v108 offset:28800
	ds_read_b64_tr_b16 v[202:203], v108 offset:29952
	ds_read_b64_tr_b16 v[204:205], v108 offset:31104
	v_mfma_f32_32x32x16_bf16 v[50:65], v[190:193], v[70:73], v[50:65]
	ds_read_b64_tr_b16 v[206:207], v108 offset:32256
	ds_read_b64_tr_b16 v[208:209], v108 offset:33408
	ds_read_b64_tr_b16 v[210:211], v108 offset:34560
	ds_read_b64_tr_b16 v[212:213], v108 offset:35712
	v_mfma_f32_32x32x16_bf16 v[50:65], v[242:245], v[74:77], v[50:65]
	ds_read_b64_tr_b16 v[214:215], v108 offset:27712
	ds_read_b64_tr_b16 v[216:217], v108 offset:28864
	ds_read_b64_tr_b16 v[218:219], v108 offset:30016
	ds_read_b64_tr_b16 v[220:221], v108 offset:31168
	v_mfma_f32_32x32x16_bf16 v[50:65], v[246:249], v[78:81], v[50:65]
	ds_read_b64_tr_b16 v[234:235], v108 offset:32320
	ds_read_b64_tr_b16 v[236:237], v108 offset:33472
	ds_read_b64_tr_b16 v[238:239], v108 offset:34624
	ds_read_b64_tr_b16 v[240:241], v108 offset:35776
	s_nop 1
	s_cmp_lg_u32 s11, s13
	s_cbranch_scc1 .LBB0_835
	v_subrev_u32_e32 v104, 27, v111
	v_subrev_u32_e32 v1, 59, v111
	v_cmp_le_i32_e32 vcc, v104, v102
	s_nop 7
	v_cndmask_b32_e32 v50, v232, v50, vcc
	v_cmp_lt_i32_e32 vcc, v1, v102
	s_nop 1
	v_cndmask_b32_e32 v35, v232, v35, vcc
	v_cmp_le_i32_e32 vcc, v1, v102
	v_subrev_u32_e32 v1, 26, v111
	s_nop 0
	v_cndmask_b32_e32 v34, v232, v34, vcc
	v_cmp_le_i32_e32 vcc, v1, v102
	v_subrev_u32_e32 v1, 57, v111
	s_nop 0
	v_cndmask_b32_e32 v51, v232, v51, vcc
	v_cmp_le_i32_e32 vcc, v1, v102
	v_subrev_u32_e32 v1, 25, v111
	s_nop 0
	v_cndmask_b32_e32 v36, v232, v36, vcc
	v_cmp_le_i32_e32 vcc, v1, v102
	v_subrev_u32_e32 v1, 56, v111
	s_nop 0
	v_cndmask_b32_e32 v52, v232, v52, vcc
	v_cmp_le_i32_e32 vcc, v1, v102
	v_subrev_u32_e32 v1, 24, v111
	s_nop 0
	v_cndmask_b32_e32 v37, v232, v37, vcc
	v_cmp_le_i32_e32 vcc, v1, v102
	v_subrev_u32_e32 v1, 51, v111
	s_nop 0
	v_cndmask_b32_e32 v53, v232, v53, vcc
	v_cmp_le_i32_e32 vcc, v1, v102
	v_subrev_u32_e32 v1, 19, v111
	s_nop 0
	v_cndmask_b32_e32 v38, v232, v38, vcc
	v_cmp_le_i32_e32 vcc, v1, v102
	v_subrev_u32_e32 v1, 50, v111
	s_nop 0
	v_cndmask_b32_e32 v54, v232, v54, vcc
	v_cmp_le_i32_e32 vcc, v1, v102
	v_subrev_u32_e32 v1, 18, v111
	s_nop 0
	v_cndmask_b32_e32 v39, v232, v39, vcc
	v_cmp_le_i32_e32 vcc, v1, v102
	v_subrev_u32_e32 v1, 49, v111
	s_nop 0
	v_cndmask_b32_e32 v55, v232, v55, vcc
	v_cmp_le_i32_e32 vcc, v1, v102
	v_subrev_u32_e32 v1, 17, v111
	s_nop 0
	v_cndmask_b32_e32 v40, v232, v40, vcc
	v_cmp_le_i32_e32 vcc, v1, v102
	v_subrev_u32_e32 v1, 48, v111
	s_nop 0
	v_cndmask_b32_e32 v56, v232, v56, vcc
	v_cmp_le_i32_e32 vcc, v1, v102
	v_add_u32_e32 v1, -16, v111
	s_nop 0
	v_cndmask_b32_e32 v41, v232, v41, vcc
	v_cmp_le_i32_e32 vcc, v1, v102
	v_subrev_u32_e32 v1, 43, v111
	s_nop 0
	v_cndmask_b32_e32 v57, v232, v57, vcc
	v_cmp_le_i32_e32 vcc, v1, v102
	v_add_u32_e32 v1, -11, v111
	s_nop 0
	v_cndmask_b32_e32 v42, v232, v42, vcc
	v_cmp_le_i32_e32 vcc, v1, v102
	v_subrev_u32_e32 v1, 42, v111
	s_nop 0
	v_cndmask_b32_e32 v58, v232, v58, vcc
	v_cmp_le_i32_e32 vcc, v1, v102
	v_add_u32_e32 v1, -10, v111
	s_nop 0
	v_cndmask_b32_e32 v43, v232, v43, vcc
	v_cmp_le_i32_e32 vcc, v1, v102
	v_subrev_u32_e32 v1, 41, v111
	s_nop 0
	v_cndmask_b32_e32 v59, v232, v59, vcc
	v_cmp_le_i32_e32 vcc, v1, v102
	v_add_u32_e32 v1, -9, v111
	s_nop 0
	v_cndmask_b32_e32 v44, v232, v44, vcc
	v_cmp_le_i32_e32 vcc, v1, v102
	v_subrev_u32_e32 v1, 40, v111
	s_nop 0
	v_cndmask_b32_e32 v60, v232, v60, vcc
	v_cmp_le_i32_e32 vcc, v1, v102
	v_add_u32_e32 v1, -8, v111
	s_nop 0
	v_cndmask_b32_e32 v45, v232, v45, vcc
	v_cmp_le_i32_e32 vcc, v1, v102
	v_subrev_u32_e32 v1, 35, v111
	s_nop 0
	v_cndmask_b32_e32 v61, v232, v61, vcc
	v_cmp_le_i32_e32 vcc, v1, v102
	v_add_u32_e32 v1, -3, v111
	s_nop 0
	v_cndmask_b32_e32 v46, v232, v46, vcc
	v_cmp_le_i32_e32 vcc, v1, v102
	v_subrev_u32_e32 v1, 34, v111
	s_nop 0
	v_cndmask_b32_e32 v62, v232, v62, vcc
	v_cmp_le_i32_e32 vcc, v1, v102
	v_add_u32_e32 v1, -2, v111
	s_nop 0
	v_cndmask_b32_e32 v47, v232, v47, vcc
	v_cmp_le_i32_e32 vcc, v1, v102
	v_subrev_u32_e32 v1, 33, v111
	s_nop 0
	v_cndmask_b32_e32 v63, v232, v63, vcc
	v_cmp_le_i32_e32 vcc, v1, v102
	v_add_u32_e32 v1, -1, v111
	s_nop 0
	v_cndmask_b32_e32 v48, v232, v48, vcc
	v_cmp_le_i32_e32 vcc, v1, v102
	v_subrev_u32_e32 v1, 32, v111
	s_nop 0
	v_cndmask_b32_e32 v64, v232, v64, vcc
	v_cmp_le_i32_e32 vcc, v1, v102
	s_nop 1
	v_cndmask_b32_e32 v49, v232, v49, vcc
	v_cmp_le_i32_e32 vcc, v111, v102
	s_nop 1
	v_cndmask_b32_e32 v65, v232, v65, vcc
